# Resid epilogue: second row-half residual loads hoisted above first-half stores/atomics; no mid-epilogue vmcnt drains
# baseline (speedup 1.0000x reference)
.LBB0_500:
	s_lshl_b32 s2, s85, 8
	v_mov_b32_e32 v128, v199
	v_mov_b32_e32 v129, v200
	s_add_i32 s2, s2, s65
	s_nop 0
	v_add_u32_e32 v192, s2, v129
	s_lshl_b32 s2, s84, 8
	s_or_b32 s2, s2, s79
	v_lshl_add_u32 v180, v128, 3, s2
	v_ashrrev_i32_e32 v181, 31, v180
	v_lshlrev_b64 v[208:209], 1, v[180:181]
	v_ashrrev_i32_e32 v193, 31, v192
	v_lshl_add_u64 v[182:183], s[30:31], 0, v[208:209]
	v_lshlrev_b64 v[184:185], 11, v[192:193]
	v_cmp_eq_u32_e32 vcc, 0, v128
	v_lshl_add_u64 v[128:129], v[182:183], 0, v[184:185]
	global_load_dwordx4 v[204:207], v[128:129], off
	global_load_dwordx4 v[152:155], v[128:129], off offset:256
	s_mov_b64 s[2:3], 0x8000
	v_lshl_add_u64 v[190:191], v[184:185], 0, s[2:3]
	s_mov_b64 s[2:3], 0x10000
	v_lshl_add_u64 v[128:129], v[182:183], 0, v[190:191]
	v_lshl_add_u64 v[188:189], v[184:185], 0, s[2:3]
	s_mov_b64 s[2:3], 0x18000
	global_load_dwordx4 v[148:151], v[128:129], off
	global_load_dwordx4 v[144:147], v[128:129], off offset:256
	v_lshl_add_u64 v[128:129], v[182:183], 0, v[188:189]
	v_lshl_add_u64 v[186:187], v[184:185], 0, s[2:3]
	global_load_dwordx4 v[140:143], v[128:129], off
	global_load_dwordx4 v[136:139], v[128:129], off offset:256
	v_lshl_add_u64 v[128:129], v[182:183], 0, v[186:187]
	global_load_dwordx4 v[132:135], v[128:129], off
	s_nop 0
	global_load_dwordx4 v[128:131], v[128:129], off offset:256
	s_waitcnt vmcnt(0)
	s_mov_b64 s[2:3], 0x40000
	v_lshl_add_u64 v[218:219], v[184:185], 0, s[2:3]
	v_lshl_add_u64 v[218:219], v[182:183], 0, v[218:219]
	global_load_dwordx4 v[220:223], v[218:219], off
	global_load_dwordx4 v[224:227], v[218:219], off offset:256
	s_mov_b64 s[2:3], 0x48000
	v_lshl_add_u64 v[218:219], v[184:185], 0, s[2:3]
	v_lshl_add_u64 v[218:219], v[182:183], 0, v[218:219]
	global_load_dwordx4 v[228:231], v[218:219], off
	global_load_dwordx4 v[232:235], v[218:219], off offset:256
	s_mov_b64 s[2:3], 0x50000
	v_lshl_add_u64 v[218:219], v[184:185], 0, s[2:3]
	v_lshl_add_u64 v[218:219], v[182:183], 0, v[218:219]
	global_load_dwordx4 v[236:239], v[218:219], off
	global_load_dwordx4 v[244:247], v[218:219], off offset:256
	s_mov_b64 s[2:3], 0x58000
	v_lshl_add_u64 v[218:219], v[184:185], 0, s[2:3]
	v_lshl_add_u64 v[218:219], v[182:183], 0, v[218:219]
	global_load_dwordx4 v[248:251], v[218:219], off
	global_load_dwordx4 v[252:255], v[218:219], off offset:256
	v_lshlrev_b32_e32 v210, 16, v204
	v_and_b32_e32 v211, 0xffff0000, v204
	v_lshlrev_b32_e32 v204, 16, v205
	v_and_b32_e32 v205, 0xffff0000, v205
	v_pk_fma_f32 v[212:213], v[174:175], v[126:127], v[204:205]
	v_lshlrev_b32_e32 v204, 16, v206
	v_and_b32_e32 v205, 0xffff0000, v206
	v_pk_fma_f32 v[210:211], v[174:175], v[124:125], v[210:211]
	v_pk_fma_f32 v[214:215], v[174:175], v[120:121], v[204:205]
	v_lshlrev_b32_e32 v204, 16, v207
	v_and_b32_e32 v205, 0xffff0000, v207
	v_pk_mul_f32 v[124:125], v[210:211], v[210:211]
	v_pk_fma_f32 v[216:217], v[174:175], v[122:123], v[204:205]
	v_cvt_pk_bf16_f32 v204, v210, v211
	v_lshl_add_u64 v[210:211], s[30:31], 0, v[184:185]
	v_pk_mul_f32 v[126:127], v[212:213], v[212:213]
	v_pk_mul_f32 v[122:123], v[216:217], v[216:217]
	v_cvt_pk_bf16_f32 v205, v212, v213
	v_cvt_pk_bf16_f32 v206, v214, v215
	v_cvt_pk_bf16_f32 v207, v216, v217
	v_lshl_add_u64 v[208:209], v[210:211], 0, v[208:209]
	v_pk_mul_f32 v[120:121], v[214:215], v[214:215]
	global_store_dwordx4 v[208:209], v[204:207], off
	v_add_f32_e32 v122, v123, v122
	v_add_f32_e32 v123, v127, v126
	v_lshlrev_b32_e32 v204, 16, v152
	v_and_b32_e32 v205, 0xffff0000, v152
	v_add_f32_e32 v124, v125, v124
	v_pk_fma_f32 v[116:117], v[174:175], v[116:117], v[204:205]
	v_lshlrev_b32_e32 v152, 16, v153
	v_and_b32_e32 v153, 0xffff0000, v153
	v_add_f32_e32 v123, v124, v123
	v_add_f32_e32 v120, v121, v120
	v_pk_mul_f32 v[204:205], v[116:117], v[116:117]
	v_pk_fma_f32 v[118:119], v[174:175], v[118:119], v[152:153]
	v_lshlrev_b32_e32 v206, 16, v154
	v_and_b32_e32 v207, 0xffff0000, v154
	v_add_f32_e32 v120, v120, v123
	v_pk_mul_f32 v[152:153], v[118:119], v[118:119]
	v_pk_fma_f32 v[206:207], v[174:175], v[112:113], v[206:207]
	v_lshlrev_b32_e32 v154, 16, v155
	v_and_b32_e32 v155, 0xffff0000, v155
	v_add_f32_e32 v120, v122, v120
	v_add_f32_e32 v121, v205, v204
	v_pk_mul_f32 v[112:113], v[206:207], v[206:207]
	v_pk_fma_f32 v[154:155], v[174:175], v[114:115], v[154:155]
	v_add_f32_e32 v120, v121, v120
	v_add_f32_e32 v121, v153, v152
	v_pk_mul_f32 v[114:115], v[154:155], v[154:155]
	v_add_f32_e32 v120, v121, v120
	v_add_f32_e32 v112, v113, v112
	v_add_f32_e32 v112, v112, v120
	v_add_f32_e32 v113, v115, v114
	v_add_f32_e32 v120, v113, v112
	v_cvt_pk_bf16_f32 v112, v116, v117
	v_cvt_pk_bf16_f32 v113, v118, v119
	v_cvt_pk_bf16_f32 v114, v206, v207
	v_cvt_pk_bf16_f32 v115, v154, v155
	global_store_dwordx4 v[208:209], v[112:115], off offset:256
	ds_bpermute_b32 v112, v157, v120
	s_waitcnt lgkmcnt(0)
	v_add_f32_e32 v116, v120, v112
	ds_bpermute_b32 v117, v194, v116
	v_mov_b64_e32 v[114:115], 0
	v_lshl_add_u64 v[112:113], v[192:193], 3, s[6:7]
	s_and_saveexec_b64 s[34:35], vcc
	s_cbranch_execz .LBB0_502
	s_waitcnt lgkmcnt(0)
	v_add_f32_e32 v114, v116, v117
	v_mul_f32_e32 v114, 0x49800000, v114
	v_trunc_f32_e32 v114, v114
	v_mul_f32_e64 v115, |v114|, s70
	v_floor_f32_e32 v115, v115
	v_fma_f32 v116, v115, s71, |v114|
	v_cvt_u32_f32_e32 v116, v116
	v_cvt_u32_f32_e32 v115, v115
	v_ashrrev_i32_e32 v117, 31, v114
	v_xor_b32_e32 v114, v116, v117
	v_xor_b32_e32 v115, v115, v117
	v_sub_co_u32_e64 v114, s[2:3], v114, v117
	s_nop 1
	v_subb_co_u32_e64 v115, s[2:3], v115, v117, s[2:3]
	global_atomic_add_x2 v[112:113], v[114:115], off

.LBB0_508:
	s_or_b64 exec, exec, s[34:35]
	s_mov_b64 s[2:3], 0x40000
	v_lshl_add_u64 v[102:103], v[184:185], 0, s[2:3]
	s_waitcnt lgkmcnt(0)
	v_lshl_add_u64 v[64:65], v[182:183], 0, v[102:103]
	s_waitcnt vmcnt(8)
	v_mov_b32_e32 v94, v220
	v_mov_b32_e32 v95, v221
	v_mov_b32_e32 v96, v222
	v_mov_b32_e32 v97, v223
	v_mov_b32_e32 v98, v224
	v_mov_b32_e32 v99, v225
	v_mov_b32_e32 v100, v226
	v_mov_b32_e32 v101, v227
	s_mov_b64 s[2:3], 0x48000
	v_lshl_add_u64 v[92:93], v[184:185], 0, s[2:3]
	s_mov_b64 s[2:3], 0x50000
	v_lshl_add_u64 v[64:65], v[182:183], 0, v[92:93]
	v_lshl_add_u64 v[90:91], v[184:185], 0, s[2:3]
	s_mov_b64 s[2:3], 0x58000
	v_mov_b32_e32 v84, v228
	v_mov_b32_e32 v85, v229
	v_mov_b32_e32 v86, v230
	v_mov_b32_e32 v87, v231
	v_mov_b32_e32 v80, v232
	v_mov_b32_e32 v81, v233
	v_mov_b32_e32 v82, v234
	v_mov_b32_e32 v83, v235
	v_lshl_add_u64 v[64:65], v[182:183], 0, v[90:91]
	v_lshl_add_u64 v[88:89], v[184:185], 0, s[2:3]
	v_mov_b32_e32 v76, v236
	v_mov_b32_e32 v77, v237
	v_mov_b32_e32 v78, v238
	v_mov_b32_e32 v79, v239
	v_mov_b32_e32 v72, v244
	v_mov_b32_e32 v73, v245
	v_mov_b32_e32 v74, v246
	v_mov_b32_e32 v75, v247
	v_lshl_add_u64 v[64:65], v[182:183], 0, v[88:89]
	v_mov_b32_e32 v68, v248
	v_mov_b32_e32 v69, v249
	v_mov_b32_e32 v70, v250
	v_mov_b32_e32 v71, v251
	s_nop 0
	v_mov_b32_e32 v64, v252
	v_mov_b32_e32 v65, v253
	v_mov_b32_e32 v66, v254
	v_mov_b32_e32 v67, v255
	v_lshlrev_b32_e32 v104, 16, v94
	v_and_b32_e32 v105, 0xffff0000, v94
	v_lshlrev_b32_e32 v106, 16, v96
	v_and_b32_e32 v107, 0xffff0000, v96
	v_pk_fma_f32 v[60:61], v[174:175], v[60:61], v[104:105]
	v_lshlrev_b32_e32 v94, 16, v95
	v_and_b32_e32 v95, 0xffff0000, v95
	v_pk_fma_f32 v[106:107], v[174:175], v[56:57], v[106:107]
	v_lshlrev_b32_e32 v56, 16, v97
	v_and_b32_e32 v57, 0xffff0000, v97
	v_pk_mul_f32 v[104:105], v[60:61], v[60:61]
	v_pk_fma_f32 v[62:63], v[174:175], v[62:63], v[94:95]
	v_pk_fma_f32 v[96:97], v[174:175], v[58:59], v[56:57]
	v_cvt_pk_bf16_f32 v56, v60, v61
	v_lshl_add_u64 v[60:61], s[30:31], 0, v[102:103]
	v_pk_mul_f32 v[94:95], v[62:63], v[62:63]
	v_cvt_pk_bf16_f32 v57, v62, v63
	v_cvt_pk_bf16_f32 v58, v106, v107
	v_cvt_pk_bf16_f32 v59, v96, v97
	v_lshl_add_u64 v[60:61], v[180:181], 1, v[60:61]
	v_pk_mul_f32 v[108:109], v[106:107], v[106:107]
	global_store_dwordx4 v[60:61], v[56:59], off
	v_add_f32_e32 v94, v95, v94
	v_add_f32_e32 v95, v105, v104
	v_lshlrev_b32_e32 v56, 16, v98
	v_and_b32_e32 v57, 0xffff0000, v98
	v_pk_mul_f32 v[110:111], v[96:97], v[96:97]
	v_pk_fma_f32 v[52:53], v[174:175], v[52:53], v[56:57]
	v_lshlrev_b32_e32 v58, 16, v99
	v_and_b32_e32 v59, 0xffff0000, v99
	v_add_f32_e32 v94, v95, v94
	v_add_f32_e32 v95, v109, v108
	v_pk_mul_f32 v[56:57], v[52:53], v[52:53]
	v_pk_fma_f32 v[54:55], v[174:175], v[54:55], v[58:59]
	v_lshlrev_b32_e32 v62, 16, v100
	v_and_b32_e32 v63, 0xffff0000, v100
	v_add_f32_e32 v94, v95, v94
	v_add_f32_e32 v95, v111, v110
	v_pk_mul_f32 v[58:59], v[54:55], v[54:55]
	v_pk_fma_f32 v[62:63], v[174:175], v[48:49], v[62:63]
	v_lshlrev_b32_e32 v96, 16, v101
	v_and_b32_e32 v97, 0xffff0000, v101
	v_add_f32_e32 v94, v95, v94
	v_add_f32_e32 v56, v57, v56
	v_pk_mul_f32 v[48:49], v[62:63], v[62:63]
	v_pk_fma_f32 v[96:97], v[174:175], v[50:51], v[96:97]
	v_add_f32_e32 v56, v56, v94
	v_add_f32_e32 v57, v59, v58
	v_pk_mul_f32 v[50:51], v[96:97], v[96:97]
	v_add_f32_e32 v56, v57, v56
	v_add_f32_e32 v48, v49, v48
	v_add_f32_e32 v48, v48, v56
	v_add_f32_e32 v49, v51, v50
	v_add_f32_e32 v56, v49, v48
	v_cvt_pk_bf16_f32 v48, v52, v53
	v_cvt_pk_bf16_f32 v49, v54, v55
	v_cvt_pk_bf16_f32 v50, v62, v63
	v_cvt_pk_bf16_f32 v51, v96, v97
	global_store_dwordx4 v[60:61], v[48:51], off offset:256
	ds_bpermute_b32 v48, v157, v56
	s_waitcnt lgkmcnt(0)
	v_add_f32_e32 v48, v56, v48
	ds_bpermute_b32 v49, v194, v48
	s_and_saveexec_b64 s[34:35], vcc
	s_cbranch_execz .LBB0_510
	s_waitcnt lgkmcnt(0)
	v_add_f32_e32 v48, v48, v49
	v_mul_f32_e32 v48, 0x49800000, v48
	v_trunc_f32_e32 v48, v48
	v_mul_f32_e64 v49, |v48|, s70
	v_floor_f32_e32 v49, v49
	v_fma_f32 v50, v49, s71, |v48|
	v_cvt_u32_f32_e32 v50, v50
	v_cvt_u32_f32_e32 v49, v49
	v_ashrrev_i32_e32 v51, 31, v48
	v_xor_b32_e32 v48, v50, v51
	v_xor_b32_e32 v49, v49, v51
	v_sub_co_u32_e64 v48, s[2:3], v48, v51
	s_nop 1
	v_subb_co_u32_e64 v49, s[2:3], v49, v51, s[2:3]
	global_atomic_add_x2 v[112:113], v[48:49], off offset:1024
.LBB0_510:
	s_or_b64 exec, exec, s[34:35]
	v_lshlrev_b32_e32 v48, 16, v84
	s_waitcnt lgkmcnt(0)
	v_and_b32_e32 v49, 0xffff0000, v84
	v_lshlrev_b32_e32 v50, 16, v85
	v_and_b32_e32 v51, 0xffff0000, v85
	v_pk_fma_f32 v[44:45], v[174:175], v[44:45], v[48:49]
	v_pk_fma_f32 v[46:47], v[174:175], v[46:47], v[50:51]
	v_lshlrev_b32_e32 v52, 16, v86
	v_and_b32_e32 v53, 0xffff0000, v86
	v_pk_mul_f32 v[48:49], v[44:45], v[44:45]
	v_pk_mul_f32 v[50:51], v[46:47], v[46:47]
	v_pk_fma_f32 v[52:53], v[174:175], v[40:41], v[52:53]
	v_lshlrev_b32_e32 v40, 16, v87
	v_and_b32_e32 v41, 0xffff0000, v87
	v_pk_mul_f32 v[54:55], v[52:53], v[52:53]
	v_pk_fma_f32 v[56:57], v[174:175], v[42:43], v[40:41]
	v_cvt_pk_bf16_f32 v40, v44, v45
	v_lshlrev_b32_e32 v44, 16, v80
	v_and_b32_e32 v45, 0xffff0000, v80
	v_add_f32_e32 v50, v51, v50
	v_add_f32_e32 v48, v49, v48
	v_pk_mul_f32 v[58:59], v[56:57], v[56:57]
	v_cvt_pk_bf16_f32 v41, v46, v47
	v_pk_fma_f32 v[36:37], v[174:175], v[36:37], v[44:45]
	v_lshlrev_b32_e32 v46, 16, v81
	v_and_b32_e32 v47, 0xffff0000, v81
	v_add_f32_e32 v48, v48, v50
	v_add_f32_e32 v49, v55, v54
	v_cvt_pk_bf16_f32 v42, v52, v53
	v_pk_mul_f32 v[44:45], v[36:37], v[36:37]
	v_pk_fma_f32 v[38:39], v[174:175], v[38:39], v[46:47]
	v_lshlrev_b32_e32 v52, 16, v82
	v_and_b32_e32 v53, 0xffff0000, v82
	v_add_f32_e32 v58, v59, v58
	v_add_f32_e32 v48, v49, v48
	v_cvt_pk_bf16_f32 v43, v56, v57
	v_pk_mul_f32 v[46:47], v[38:39], v[38:39]
	v_pk_fma_f32 v[52:53], v[174:175], v[32:33], v[52:53]
	v_lshlrev_b32_e32 v56, 16, v83
	v_and_b32_e32 v57, 0xffff0000, v83
	v_add_f32_e32 v48, v58, v48
	v_add_f32_e32 v44, v45, v44
	v_pk_mul_f32 v[32:33], v[52:53], v[52:53]
	v_pk_fma_f32 v[56:57], v[174:175], v[34:35], v[56:57]
	v_add_f32_e32 v44, v44, v48
	v_add_f32_e32 v45, v47, v46
	v_pk_mul_f32 v[34:35], v[56:57], v[56:57]
	v_add_f32_e32 v44, v45, v44
	v_add_f32_e32 v32, v33, v32
	v_add_f32_e32 v32, v32, v44
	v_add_f32_e32 v33, v35, v34
	v_add_f32_e32 v35, v33, v32
	ds_bpermute_b32 v46, v157, v35
	v_lshl_add_u64 v[32:33], s[30:31], 0, v[92:93]
	v_lshl_add_u64 v[44:45], v[180:181], 1, v[32:33]
	v_cvt_pk_bf16_f32 v34, v36, v37
	v_cvt_pk_bf16_f32 v36, v52, v53
	s_waitcnt lgkmcnt(0)
	v_add_f32_e32 v32, v35, v46
	ds_bpermute_b32 v33, v194, v32
	v_cvt_pk_bf16_f32 v35, v38, v39
	v_cvt_pk_bf16_f32 v37, v56, v57
	global_store_dwordx4 v[44:45], v[40:43], off
	global_store_dwordx4 v[44:45], v[34:37], off offset:256
	s_and_saveexec_b64 s[34:35], vcc
	s_cbranch_execz .LBB0_512
	s_waitcnt lgkmcnt(0)
	v_add_f32_e32 v32, v32, v33
	v_mul_f32_e32 v32, 0x49800000, v32
	v_trunc_f32_e32 v32, v32
	v_mul_f32_e64 v33, |v32|, s70
	v_floor_f32_e32 v33, v33
	v_fma_f32 v34, v33, s71, |v32|
	v_cvt_u32_f32_e32 v34, v34
	v_cvt_u32_f32_e32 v33, v33
	v_ashrrev_i32_e32 v35, 31, v32
	v_xor_b32_e32 v32, v34, v35
	v_xor_b32_e32 v33, v33, v35
	v_sub_co_u32_e64 v32, s[2:3], v32, v35
	s_nop 1
	v_subb_co_u32_e64 v33, s[2:3], v33, v35, s[2:3]
	global_atomic_add_x2 v[112:113], v[32:33], off offset:1152
.LBB0_512:
	s_or_b64 exec, exec, s[34:35]
	v_lshlrev_b32_e32 v32, 16, v76
	s_waitcnt lgkmcnt(0)
	v_and_b32_e32 v33, 0xffff0000, v76
	v_lshlrev_b32_e32 v34, 16, v77
	v_and_b32_e32 v35, 0xffff0000, v77
	v_pk_fma_f32 v[28:29], v[174:175], v[28:29], v[32:33]
	v_pk_fma_f32 v[30:31], v[174:175], v[30:31], v[34:35]
	v_lshlrev_b32_e32 v36, 16, v78
	v_and_b32_e32 v37, 0xffff0000, v78
	v_pk_mul_f32 v[32:33], v[28:29], v[28:29]
	v_pk_mul_f32 v[34:35], v[30:31], v[30:31]
	v_pk_fma_f32 v[36:37], v[174:175], v[24:25], v[36:37]
	v_lshlrev_b32_e32 v24, 16, v79
	v_and_b32_e32 v25, 0xffff0000, v79
	v_pk_mul_f32 v[38:39], v[36:37], v[36:37]
	v_pk_fma_f32 v[40:41], v[174:175], v[26:27], v[24:25]
	v_cvt_pk_bf16_f32 v24, v28, v29
	v_lshlrev_b32_e32 v28, 16, v72
	v_and_b32_e32 v29, 0xffff0000, v72
	v_add_f32_e32 v34, v35, v34
	v_add_f32_e32 v32, v33, v32
	v_pk_mul_f32 v[42:43], v[40:41], v[40:41]
	v_cvt_pk_bf16_f32 v25, v30, v31
	v_pk_fma_f32 v[20:21], v[174:175], v[20:21], v[28:29]
	v_lshlrev_b32_e32 v30, 16, v73
	v_and_b32_e32 v31, 0xffff0000, v73
	v_add_f32_e32 v32, v32, v34
	v_add_f32_e32 v33, v39, v38
	v_cvt_pk_bf16_f32 v26, v36, v37
	v_pk_mul_f32 v[28:29], v[20:21], v[20:21]
	v_pk_fma_f32 v[22:23], v[174:175], v[22:23], v[30:31]
	v_lshlrev_b32_e32 v36, 16, v74
	v_and_b32_e32 v37, 0xffff0000, v74
	v_add_f32_e32 v42, v43, v42
	v_add_f32_e32 v32, v33, v32
	v_cvt_pk_bf16_f32 v27, v40, v41
	v_pk_mul_f32 v[30:31], v[22:23], v[22:23]
	v_pk_fma_f32 v[36:37], v[174:175], v[16:17], v[36:37]
	v_lshlrev_b32_e32 v40, 16, v75
	v_and_b32_e32 v41, 0xffff0000, v75
	v_add_f32_e32 v32, v42, v32
	v_add_f32_e32 v28, v29, v28
	v_pk_mul_f32 v[16:17], v[36:37], v[36:37]
	v_pk_fma_f32 v[40:41], v[174:175], v[18:19], v[40:41]
	v_add_f32_e32 v28, v28, v32
	v_add_f32_e32 v29, v31, v30
	v_pk_mul_f32 v[18:19], v[40:41], v[40:41]
	v_add_f32_e32 v28, v29, v28
	v_add_f32_e32 v16, v17, v16
	v_add_f32_e32 v16, v16, v28
	v_add_f32_e32 v17, v19, v18
	v_add_f32_e32 v19, v17, v16
	ds_bpermute_b32 v30, v157, v19
	v_lshl_add_u64 v[16:17], s[30:31], 0, v[90:91]
	v_lshl_add_u64 v[28:29], v[180:181], 1, v[16:17]
	v_cvt_pk_bf16_f32 v18, v20, v21
	v_cvt_pk_bf16_f32 v20, v36, v37
	s_waitcnt lgkmcnt(0)
	v_add_f32_e32 v16, v19, v30
	ds_bpermute_b32 v17, v194, v16
	v_cvt_pk_bf16_f32 v19, v22, v23
	v_cvt_pk_bf16_f32 v21, v40, v41
	global_store_dwordx4 v[28:29], v[24:27], off
	global_store_dwordx4 v[28:29], v[18:21], off offset:256
	s_and_saveexec_b64 s[34:35], vcc
	s_cbranch_execz .LBB0_514
	s_waitcnt lgkmcnt(0)
	v_add_f32_e32 v16, v16, v17
	v_mul_f32_e32 v16, 0x49800000, v16
	v_trunc_f32_e32 v16, v16
	v_mul_f32_e64 v17, |v16|, s70
	v_floor_f32_e32 v17, v17
	v_fma_f32 v18, v17, s71, |v16|
	v_cvt_u32_f32_e32 v18, v18
	v_cvt_u32_f32_e32 v17, v17
	v_ashrrev_i32_e32 v19, 31, v16
	v_xor_b32_e32 v16, v18, v19
	v_xor_b32_e32 v17, v17, v19
	v_sub_co_u32_e64 v16, s[2:3], v16, v19
	s_nop 1
	v_subb_co_u32_e64 v17, s[2:3], v17, v19, s[2:3]
	global_atomic_add_x2 v[112:113], v[16:17], off offset:1280
.LBB0_514:
	s_or_b64 exec, exec, s[34:35]
	v_lshlrev_b32_e32 v16, 16, v68
	s_waitcnt lgkmcnt(0)
	v_and_b32_e32 v17, 0xffff0000, v68
	v_lshlrev_b32_e32 v18, 16, v69
	v_and_b32_e32 v19, 0xffff0000, v69
	v_pk_fma_f32 v[12:13], v[174:175], v[12:13], v[16:17]
	v_pk_fma_f32 v[14:15], v[174:175], v[14:15], v[18:19]
	v_lshlrev_b32_e32 v20, 16, v70
	v_and_b32_e32 v21, 0xffff0000, v70
	v_pk_mul_f32 v[16:17], v[12:13], v[12:13]
	v_pk_mul_f32 v[18:19], v[14:15], v[14:15]
	v_pk_fma_f32 v[20:21], v[174:175], v[8:9], v[20:21]
	v_lshlrev_b32_e32 v8, 16, v71
	v_and_b32_e32 v9, 0xffff0000, v71
	v_pk_mul_f32 v[22:23], v[20:21], v[20:21]
	v_pk_fma_f32 v[24:25], v[174:175], v[10:11], v[8:9]
	v_cvt_pk_bf16_f32 v8, v12, v13
	v_lshlrev_b32_e32 v12, 16, v64
	v_and_b32_e32 v13, 0xffff0000, v64
	v_add_f32_e32 v18, v19, v18
	v_add_f32_e32 v16, v17, v16
	v_pk_mul_f32 v[26:27], v[24:25], v[24:25]
	v_cvt_pk_bf16_f32 v9, v14, v15
	v_pk_fma_f32 v[4:5], v[174:175], v[4:5], v[12:13]
	v_lshlrev_b32_e32 v14, 16, v65
	v_and_b32_e32 v15, 0xffff0000, v65
	v_add_f32_e32 v16, v16, v18
	v_add_f32_e32 v17, v23, v22
	v_cvt_pk_bf16_f32 v10, v20, v21
	v_pk_mul_f32 v[12:13], v[4:5], v[4:5]
	v_pk_fma_f32 v[6:7], v[174:175], v[6:7], v[14:15]
	v_lshlrev_b32_e32 v20, 16, v66
	v_and_b32_e32 v21, 0xffff0000, v66
	v_add_f32_e32 v26, v27, v26
	v_add_f32_e32 v16, v17, v16
	v_cvt_pk_bf16_f32 v11, v24, v25
	v_pk_mul_f32 v[14:15], v[6:7], v[6:7]
	v_pk_fma_f32 v[20:21], v[174:175], v[0:1], v[20:21]
	v_lshlrev_b32_e32 v24, 16, v67
	v_and_b32_e32 v25, 0xffff0000, v67
	v_add_f32_e32 v16, v26, v16
	v_add_f32_e32 v12, v13, v12
	v_pk_mul_f32 v[0:1], v[20:21], v[20:21]
	v_pk_fma_f32 v[24:25], v[174:175], v[2:3], v[24:25]
	v_add_f32_e32 v12, v12, v16
	v_add_f32_e32 v13, v15, v14
	v_pk_mul_f32 v[2:3], v[24:25], v[24:25]
	v_add_f32_e32 v12, v13, v12
	v_add_f32_e32 v0, v1, v0
	v_add_f32_e32 v0, v0, v12
	v_add_f32_e32 v1, v3, v2
	v_add_f32_e32 v3, v1, v0
	ds_bpermute_b32 v14, v157, v3
	v_lshl_add_u64 v[0:1], s[30:31], 0, v[88:89]
	v_lshl_add_u64 v[12:13], v[180:181], 1, v[0:1]
	v_cvt_pk_bf16_f32 v2, v4, v5
	v_cvt_pk_bf16_f32 v4, v20, v21
	s_waitcnt lgkmcnt(0)
	v_add_f32_e32 v0, v3, v14
	ds_bpermute_b32 v1, v194, v0
	v_cvt_pk_bf16_f32 v3, v6, v7
	v_cvt_pk_bf16_f32 v5, v24, v25
	global_store_dwordx4 v[12:13], v[8:11], off
	global_store_dwordx4 v[12:13], v[2:5], off offset:256
	s_and_saveexec_b64 s[2:3], vcc
	s_cbranch_execz .LBB0_516
	s_waitcnt lgkmcnt(0)
	v_add_f32_e32 v0, v0, v1
	v_mul_f32_e32 v0, 0x49800000, v0
	v_trunc_f32_e32 v0, v0
	v_mul_f32_e64 v1, |v0|, s70
	v_floor_f32_e32 v1, v1
	v_fma_f32 v2, v1, s71, |v0|
	v_cvt_u32_f32_e32 v2, v2
	v_cvt_u32_f32_e32 v1, v1
	v_ashrrev_i32_e32 v3, 31, v0
	v_xor_b32_e32 v0, v2, v3
	v_xor_b32_e32 v1, v1, v3
	v_sub_co_u32_e32 v0, vcc, v0, v3
	s_nop 1
	v_subb_co_u32_e32 v1, vcc, v1, v3, vcc
	global_atomic_add_x2 v[112:113], v[0:1], off offset:1408

	.amdhsa_kernel _Z8yoco_fwd6Params
		.amdhsa_group_segment_fixed_size 0
		.amdhsa_private_segment_fixed_size 0
		.amdhsa_kernarg_size 456
		.amdhsa_user_sgpr_count 2
		.amdhsa_user_sgpr_dispatch_ptr 0
		.amdhsa_user_sgpr_queue_ptr 0
		.amdhsa_user_sgpr_kernarg_segment_ptr 1
		.amdhsa_user_sgpr_dispatch_id 0
		.amdhsa_user_sgpr_kernarg_preload_length 0
		.amdhsa_user_sgpr_kernarg_preload_offset 0
		.amdhsa_user_sgpr_private_segment_size 0
		.amdhsa_uses_dynamic_stack 0
		.amdhsa_enable_private_segment 0
		.amdhsa_system_sgpr_workgroup_id_x 1
		.amdhsa_system_sgpr_workgroup_id_y 0
		.amdhsa_system_sgpr_workgroup_id_z 0
		.amdhsa_system_sgpr_workgroup_info 0
		.amdhsa_system_vgpr_workitem_id 2
		.amdhsa_next_free_vgpr 256
		.amdhsa_next_free_sgpr 98
		.amdhsa_accum_offset 256
		.amdhsa_reserve_vcc 1
		.amdhsa_float_round_mode_32 0
		.amdhsa_float_round_mode_16_64 0
		.amdhsa_float_denorm_mode_32 3
		.amdhsa_float_denorm_mode_16_64 3
		.amdhsa_dx10_clamp 1
		.amdhsa_ieee_mode 1
		.amdhsa_fp16_overflow 0
		.amdhsa_tg_split 0
		.amdhsa_exception_fp_ieee_invalid_op 0
		.amdhsa_exception_fp_denorm_src 0
		.amdhsa_exception_fp_ieee_div_zero 0
		.amdhsa_exception_fp_ieee_overflow 0
		.amdhsa_exception_fp_ieee_underflow 0
		.amdhsa_exception_fp_ieee_inexact 0
		.amdhsa_exception_int_div_zero 0
	.end_amdhsa_kernel

amdhsa.kernels:
  - .agpr_count:     0
    .args:
      - .offset:         0
        .size:           200
        .value_kind:     by_value
      - .offset:         200
        .size:           4
        .value_kind:     hidden_block_count_x
      - .offset:         204
        .size:           4
        .value_kind:     hidden_block_count_y
      - .offset:         208
        .size:           4
        .value_kind:     hidden_block_count_z
      - .offset:         212
        .size:           2
        .value_kind:     hidden_group_size_x
      - .offset:         214
        .size:           2
        .value_kind:     hidden_group_size_y
      - .offset:         216
        .size:           2
        .value_kind:     hidden_group_size_z
      - .offset:         218
        .size:           2
        .value_kind:     hidden_remainder_x
      - .offset:         220
        .size:           2
        .value_kind:     hidden_remainder_y
      - .offset:         222
        .size:           2
        .value_kind:     hidden_remainder_z
      - .offset:         240
        .size:           8
        .value_kind:     hidden_global_offset_x
      - .offset:         248
        .size:           8
        .value_kind:     hidden_global_offset_y
      - .offset:         256
        .size:           8
        .value_kind:     hidden_global_offset_z
      - .offset:         264
        .size:           2
        .value_kind:     hidden_grid_dims
      - .offset:         288
        .size:           8
        .value_kind:     hidden_multigrid_sync_arg
      - .offset:         320
        .size:           4
        .value_kind:     hidden_dynamic_lds_size
    .group_segment_fixed_size: 0
    .kernarg_segment_align: 8
    .kernarg_segment_size: 456
    .language:       OpenCL C
    .language_version:
      - 2
      - 0
    .max_flat_workgroup_size: 512
    .name:           _Z8yoco_fwd6Params
    .private_segment_fixed_size: 0
    .sgpr_count:     104
    .sgpr_spill_count: 130
    .symbol:         _Z8yoco_fwd6Params.kd
    .uniform_work_group_size: 1
    .uses_dynamic_stack: false
    .vgpr_count:     256
    .vgpr_spill_count: 0
    .wavefront_size: 64
